# attention loop rebalanced: exp/cvt of the next tile first half moved under the last PV block, LDS-DMA issue spread over QK block
# speedup vs baseline: 1.0454x; 1.0021x over previous
.LBB0_450:
	v_mov_b32_e32 v124, v0
	s_waitcnt vmcnt(0) lgkmcnt(0)
	s_barrier
	v_readlane_b32 s56, v197, 2
	v_and_b32_e32 v125, 63, v124
	v_lshlrev_b32_e32 v126, 2, v125
	v_readlane_b32 s62, v197, 8
	v_readlane_b32 s63, v197, 9
	v_readlane_b32 s58, v197, 4
	v_readlane_b32 s59, v197, 5
	v_readlane_b32 s60, v197, 6
	v_readlane_b32 s61, v197, 7
	v_readlane_b32 s64, v197, 10
	v_readlane_b32 s65, v197, 11
	v_readlane_b32 s66, v197, 12
	v_readlane_b32 s67, v197, 13
	v_readlane_b32 s68, v197, 14
	v_readlane_b32 s69, v197, 15
	global_load_dword v4, v126, s[62:63]
	global_load_dword v5, v126, s[64:65]
	s_nop 0
	global_load_dword v6, v126, s[66:67]
	s_nop 0
	global_load_dword v7, v126, s[68:69]
	global_load_dword v8, v126, s[58:59]
	global_load_dword v9, v126, s[60:61]
	s_ashr_i32 s4, s17, 5
	s_mul_hi_i32 s12, s17, 0x2aaaaaab
	s_lshl_b32 s5, s17, 7
	s_mul_hi_i32 s13, s4, 0x2aaaaaab
	s_lshr_b32 s18, s12, 31
	s_ashr_i32 s12, s12, 5
	v_ashrrev_i32_e32 v14, 6, v124
	v_cmp_lt_i32_e32 vcc, v115, v114
	s_and_b32 s5, s5, 0xf80
	s_lshr_b32 s19, s13, 31
	s_add_i32 s20, s12, s18
	v_and_b32_e32 v128, 3, v14
	v_cndmask_b32_e32 v2, v105, v115, vcc
	v_and_b32_e32 v15, 15, v124
	s_add_i32 s12, s13, s19
	s_lshl_b32 s13, s20, 12
	v_lshl_or_b32 v16, v128, 5, s5
	v_lshlrev_b32_e32 v122, 2, v2
	v_or3_b32 v108, v16, s13, v15
	v_cmp_lt_i32_e32 vcc, v116, v114
	s_mul_i32 s12, s12, 6
	s_sub_i32 s4, s4, s12
	v_cndmask_b32_e32 v3, v105, v116, vcc
	v_lshlrev_b32_e32 v123, 2, v3
	v_cmp_lt_i32_e32 vcc, v117, v114
	v_readlane_b32 s57, v197, 3
	v_readlane_b32 s70, v197, 16
	v_cndmask_b32_e32 v10, v105, v117, vcc
	v_lshlrev_b32_e32 v10, 2, v10
	v_cmp_lt_i32_e32 vcc, v118, v114
	v_readlane_b32 s71, v197, 17
	s_lshl_b32 s4, s4, 7
	v_cndmask_b32_e32 v11, v105, v118, vcc
	v_lshlrev_b32_e32 v11, 2, v11
	v_cmp_lt_i32_e32 vcc, v119, v114
	s_ashr_i32 s5, s4, 31
	v_readlane_b32 s56, v196, 6
	v_cndmask_b32_e32 v12, v105, v119, vcc
	v_lshlrev_b32_e32 v12, 2, v12
	v_cmp_lt_i32_e32 vcc, v120, v114
	v_ashrrev_i32_e32 v127, 8, v124
	s_lshl_b64 s[12:13], s[4:5], 1
	v_cndmask_b32_e32 v13, v105, v120, vcc
	v_lshlrev_b32_e32 v13, 2, v13
	v_readlane_b32 s60, v196, 10
	v_lshlrev_b32_e32 v2, 6, v127
	v_readlane_b32 s61, v196, 11
	s_add_u32 s18, s60, s12
	v_ashrrev_i32_e32 v3, 31, v2
	s_addc_u32 s19, s61, s13
	v_and_b32_e32 v98, 48, v124
	v_lshl_add_u64 v[2:3], v[2:3], 1, s[18:19]
	s_mov_b32 s18, 0x3f828f5c
	v_lshl_add_u64 v[2:3], v[2:3], 0, v[98:99]
	v_or_b32_e32 v106, 16, v108
	v_bfe_u32 v121, v124, 4, 2
	v_ashrrev_i32_e32 v109, 31, v108
	v_ashrrev_i32_e32 v107, 31, v106
	v_lshlrev_b32_e32 v134, 13, v127
	v_mov_b32_e32 v20, v99
	v_mov_b32_e32 v21, v99
	v_mov_b32_e32 v26, v99
	v_mov_b32_e32 v27, v99
	v_mov_b32_e32 v28, v99
	v_mov_b32_e32 v29, v99
	v_mov_b32_e32 v30, v99
	v_mov_b32_e32 v31, v99
	v_mov_b32_e32 v32, v99
	v_mov_b32_e32 v33, v99
	v_mov_b32_e32 v34, v99
	v_mov_b32_e32 v35, v99
	v_mov_b32_e32 v36, v99
	v_mov_b32_e32 v37, v99
	v_mov_b32_e32 v38, v99
	v_mov_b32_e32 v39, v99
	s_waitcnt vmcnt(4)
	v_mul_f32_e32 v16, v4, v5
	ds_bpermute_b32 v16, v122, v16
	s_waitcnt vmcnt(2)
	v_mul_f32_e32 v17, v6, v7
	s_waitcnt vmcnt(1)
	v_and_b32_e32 v18, 0x7fffffff, v8
	s_waitcnt vmcnt(0)
	v_and_b32_e32 v19, 0x7fffffff, v9
	ds_bpermute_b32 v18, v122, v18
	ds_bpermute_b32 v19, v122, v19
	ds_bpermute_b32 v17, v122, v17
	v_max_f32_e64 v8, |v8|, |v8|
	v_max_f32_e64 v9, |v9|, |v9|
	s_waitcnt lgkmcnt(3)
	v_fmac_f32_e32 v16, v4, v5
	s_waitcnt lgkmcnt(2)
	v_max_f32_e32 v4, v18, v18
	s_waitcnt lgkmcnt(1)
	v_max_f32_e32 v5, v19, v19
	v_max_f32_e32 v4, v8, v4
	v_max_f32_e32 v5, v9, v5
	ds_bpermute_b32 v8, v123, v4
	ds_bpermute_b32 v9, v123, v5
	s_waitcnt lgkmcnt(2)
	v_fmac_f32_e32 v17, v6, v7
	ds_bpermute_b32 v6, v123, v16
	ds_bpermute_b32 v7, v123, v17
	s_waitcnt lgkmcnt(3)
	v_max_f32_e32 v8, v8, v8
	s_waitcnt lgkmcnt(2)
	v_max_f32_e32 v9, v9, v9
	v_max_f32_e32 v4, v4, v8
	v_max_f32_e32 v5, v5, v9
	s_waitcnt lgkmcnt(1)
	v_add_f32_e32 v6, v16, v6
	s_waitcnt lgkmcnt(0)
	v_add_f32_e32 v7, v17, v7
	ds_bpermute_b32 v8, v10, v4
	ds_bpermute_b32 v9, v10, v5
	ds_bpermute_b32 v16, v10, v6
	ds_bpermute_b32 v17, v10, v7
	v_mov_b32_e32 v18, v99
	s_waitcnt lgkmcnt(3)
	v_max_f32_e32 v8, v8, v8
	s_waitcnt lgkmcnt(2)
	v_max_f32_e32 v9, v9, v9
	s_waitcnt lgkmcnt(1)
	v_add_f32_e32 v6, v6, v16
	s_waitcnt lgkmcnt(0)
	v_add_f32_e32 v7, v7, v17
	v_max_f32_e32 v4, v4, v8
	v_max_f32_e32 v5, v5, v9
	ds_bpermute_b32 v10, v11, v6
	ds_bpermute_b32 v16, v11, v7
	ds_bpermute_b32 v8, v11, v4
	ds_bpermute_b32 v9, v11, v5
	v_mov_b32_e32 v19, v99
	s_waitcnt lgkmcnt(3)
	v_add_f32_e32 v6, v6, v10
	s_waitcnt lgkmcnt(2)
	v_add_f32_e32 v7, v7, v16
	s_waitcnt lgkmcnt(1)
	v_max_f32_e32 v8, v8, v8
	s_waitcnt lgkmcnt(0)
	v_max_f32_e32 v9, v9, v9
	ds_bpermute_b32 v10, v12, v6
	ds_bpermute_b32 v11, v12, v7
	v_max_f32_e32 v4, v4, v8
	v_max_f32_e32 v5, v5, v9
	ds_bpermute_b32 v8, v12, v4
	ds_bpermute_b32 v9, v12, v5
	s_waitcnt lgkmcnt(3)
	v_add_f32_e32 v130, v6, v10
	s_waitcnt lgkmcnt(2)
	v_add_f32_e32 v6, v7, v11
	ds_bpermute_b32 v7, v13, v6
	s_waitcnt lgkmcnt(2)
	v_max_f32_e32 v8, v8, v8
	s_waitcnt lgkmcnt(1)
	v_max_f32_e32 v9, v9, v9
	v_max_f32_e32 v4, v4, v8
	v_max_f32_e32 v5, v5, v9
	ds_bpermute_b32 v8, v13, v4
	ds_bpermute_b32 v9, v13, v5
	s_waitcnt lgkmcnt(2)
	v_add_f32_e32 v6, v6, v7
	v_mul_f32_e32 v6, 0x3fb8aa3b, v6
	v_exp_f32_e32 v129, v6
	s_waitcnt lgkmcnt(1)
	v_max_f32_e32 v6, v8, v8
	s_waitcnt lgkmcnt(0)
	v_max_f32_e32 v7, v9, v9
	v_max_f32_e32 v4, v4, v6
	v_max_f32_e32 v5, v5, v7
	v_mul_f32_e32 v4, v4, v5
	v_mul_f32_e32 v4, 0x4138aa3b, v4
	v_fma_f32 v8, v4, s18, 0.5
	v_mad_i64_i32 v[4:5], s[18:19], v108, s14, v[2:3]
	v_mad_i64_i32 v[2:3], s[18:19], v106, s14, v[2:3]
	global_load_dwordx4 v[58:61], v[4:5], off
	global_load_dwordx4 v[50:53], v[4:5], off offset:64
	global_load_dwordx4 v[62:65], v[2:3], off
	global_load_dwordx4 v[54:57], v[2:3], off offset:64
	v_ashrrev_i32_e32 v2, 3, v124
	v_ashrrev_i32_e32 v3, 31, v2
	v_mad_i64_i32 v[4:5], s[18:19], s20, v1, v[2:3]
	v_mad_u64_u32 v[6:7], s[18:19], v4, s14, v[100:101]
	s_mul_hi_i32 s18, s20, 0x300
	s_mulk_i32 s20, 0x300
	s_add_u32 s4, s20, s4
	v_lshrrev_b32_e32 v9, 4, v124
	s_addc_u32 s5, s18, s5
	v_xor_b32_e32 v10, v9, v124
	v_lshl_add_u64 v[2:3], s[4:5], 0, v[2:3]
	v_lshlrev_b32_e32 v4, 4, v10
	v_mad_u64_u32 v[112:113], s[4:5], v2, s15, v[102:103]
	v_and_b32_e32 v98, 0x70, v4
	v_mad_i32_i24 v113, v3, s15, v113
	v_mad_i32_i24 v7, v5, s14, v7
	v_lshl_add_u64 v[2:3], v[112:113], 0, v[98:99]
	s_mov_b64 s[4:5], 0x88000
	v_lshl_add_u64 v[110:111], v[6:7], 0, s[12:13]
	v_lshl_add_u64 v[6:7], v[2:3], 0, s[4:5]
	v_readfirstlane_b32 s4, v14
	s_lshl_b32 s4, s4, 10
	s_add_i32 s4, s4, 0
	v_lshl_add_u64 v[4:5], v[110:111], 0, v[98:99]
	s_mov_b32 m0, s4
	ds_bpermute_b32 v131, v13, v130
	global_load_lds_dwordx4 v[4:5], off
	v_lshl_add_u64 v[4:5], v[4:5], 0, s[2:3]
	s_add_i32 m0, s4, 0x2000
	v_xor_b32_e32 v90, 0x80000000, v8
	global_load_lds_dwordx4 v[4:5], off
	s_add_i32 m0, s4, 0x4000
	v_bfe_u32 v4, v124, 1, 3
	global_load_lds_dwordx4 v[2:3], off
	s_add_i32 m0, s4, 0x6000
	v_lshrrev_b32_e32 v3, 1, v124
	global_load_lds_dwordx4 v[6:7], off
	v_lshlrev_b32_e32 v2, 7, v15
	v_bitop3_b32 v3, v121, v3, 7 bitop3:0x78
	v_lshl_or_b32 v133, v3, 4, v2
	v_bitop3_b32 v3, v121, v4, 4 bitop3:0x36
	v_lshl_or_b32 v132, v3, 4, v2
	v_bitop3_b32 v2, v9, 7, v124 bitop3:0x48
	v_mov_b32_e32 v91, v90
	v_mov_b32_e32 v92, v90
	v_mov_b32_e32 v93, v90
	v_lshlrev_b32_e32 v98, 4, v2
	s_mov_b32 s5, 0
	v_mov_b32_e32 v2, v99
	v_mov_b32_e32 v3, v99
	v_mov_b32_e32 v4, v99
	v_mov_b32_e32 v5, v99
	v_mov_b32_e32 v6, v99
	v_mov_b32_e32 v7, v99
	v_mov_b32_e32 v8, v99
	v_mov_b32_e32 v9, v99
	v_mov_b32_e32 v10, v99
	v_mov_b32_e32 v11, v99
	v_mov_b32_e32 v12, v99
	v_mov_b32_e32 v13, v99
	v_mov_b32_e32 v40, v99
	v_mov_b32_e32 v41, v99
	v_mov_b32_e32 v42, v99
	v_mov_b32_e32 v43, v99
	v_mov_b32_e32 v44, v99
	v_mov_b32_e32 v45, v99
	v_mov_b32_e32 v46, v99
	v_mov_b32_e32 v47, v99
	v_mov_b32_e32 v48, v99
	v_mov_b32_e32 v49, v99
	v_mov_b32_e32 v66, v99
	v_mov_b32_e32 v67, v99
	v_mov_b32_e32 v68, v99
	v_mov_b32_e32 v69, v99
	v_mov_b32_e32 v70, v99
	v_mov_b32_e32 v71, v99
	v_mov_b32_e32 v72, v99
	v_mov_b32_e32 v73, v99
	v_mov_b32_e32 v74, v99
	v_mov_b32_e32 v75, v99
	v_mov_b32_e32 v76, v99
	v_mov_b32_e32 v77, v99
	v_mov_b32_e32 v78, v99
	v_mov_b32_e32 v79, v99
	v_mov_b32_e32 v80, v99
	v_mov_b32_e32 v81, v99
	v_mov_b32_e32 v82, v99
	v_mov_b32_e32 v83, v99
	v_mov_b32_e32 v84, v99
	v_mov_b32_e32 v85, v99
	v_mov_b32_e32 v86, v99
	v_mov_b32_e32 v87, v99
	v_mov_b32_e32 v88, v99
	v_mov_b32_e32 v89, v99
	v_mov_b32_e32 v14, v99
	v_mov_b32_e32 v15, v99
	v_mov_b32_e32 v16, v99
	v_mov_b32_e32 v17, v99
	v_mov_b32_e32 v22, v99
	v_mov_b32_e32 v23, v99
	v_mov_b32_e32 v24, v99
	v_mov_b32_e32 v25, v99
	v_readlane_b32 s57, v196, 7
	v_readlane_b32 s58, v196, 8
	v_readlane_b32 s59, v196, 9
	v_readlane_b32 s62, v196, 12
	v_readlane_b32 s63, v196, 13
	v_readlane_b32 s64, v196, 14
	v_readlane_b32 s65, v196, 15
	v_readlane_b32 s66, v196, 16
	v_readlane_b32 s67, v196, 17
	v_readlane_b32 s68, v196, 18
	v_readlane_b32 s69, v196, 19
	v_readlane_b32 s70, v196, 20
	v_readlane_b32 s71, v196, 21
	s_waitcnt vmcnt(0) lgkmcnt(0)
	s_barrier
	v_lshl_add_u64 v[248:249], v[110:111], 0, v[98:99]
	v_lshl_add_u64 v[252:253], v[112:113], 0, v[98:99]
	s_mov_b64 s[26:27], 0x88000
	v_lshl_add_u64 v[248:249], v[248:249], 0, s[6:7]
	v_lshl_add_u64 v[252:253], v[252:253], 0, s[2:3]
	v_lshl_add_u64 v[250:251], v[248:249], 0, s[2:3]
	v_lshl_add_u64 v[254:255], v[252:253], 0, s[26:27]
	v_mov_b32_e32 v244, s8
	v_mov_b32_e32 v245, s9
	v_mov_b32_e32 v246, s10
	v_mov_b32_e32 v247, s11
	s_mov_b32 s20, 0x8000
	s_mov_b32 s21, 0
	s_mov_b32 s22, 0x10000
	s_mov_b32 s23, 0
	s_add_i32 s25, s4, s20
	s_mov_b32 m0, s25
	s_nop 0
	global_load_lds_dwordx4 v[248:249], off
	s_add_i32 m0, s25, 0x2000
	s_nop 0
	global_load_lds_dwordx4 v[250:251], off
	s_add_i32 m0, s25, 0x4000
	s_nop 0
	global_load_lds_dwordx4 v[252:253], off
	s_add_i32 m0, s25, 0x6000
	s_nop 0
	global_load_lds_dwordx4 v[254:255], off
	v_lshl_add_u64 v[248:249], v[248:249], 0, s[6:7]
	v_lshl_add_u64 v[250:251], v[250:251], 0, s[6:7]
	v_lshl_add_u64 v[252:253], v[252:253], 0, s[2:3]
	v_lshl_add_u64 v[254:255], v[254:255], 0, s[2:3]
	v_add_u32_e32 v94, v134, v133
	v_add_u32_e32 v95, v134, v132
	ds_read_b128 v[204:207], v94
	ds_read_b128 v[208:211], v95
	ds_read_b128 v[212:215], v94 offset:2048
	ds_read_b128 v[216:219], v95 offset:2048
	s_waitcnt lgkmcnt(3)
	v_mfma_f32_16x16x32_bf16 v[136:139], v[204:207], v[58:61], v[90:93]
	v_mfma_f32_16x16x32_bf16 v[140:143], v[204:207], v[62:65], v[90:93]
	ds_read_b128 v[204:207], v94 offset:4096
	s_waitcnt lgkmcnt(3)
	v_mfma_f32_16x16x32_bf16 v[136:139], v[208:211], v[50:53], v[136:139]
	v_mfma_f32_16x16x32_bf16 v[140:143], v[208:211], v[54:57], v[140:143]
	ds_read_b128 v[208:211], v95 offset:4096
	s_waitcnt lgkmcnt(3)
	v_mfma_f32_16x16x32_bf16 v[144:147], v[212:215], v[58:61], v[90:93]
	v_mfma_f32_16x16x32_bf16 v[148:151], v[212:215], v[62:65], v[90:93]
	ds_read_b128 v[212:215], v94 offset:6144
	s_waitcnt lgkmcnt(3)
	v_mfma_f32_16x16x32_bf16 v[144:147], v[216:219], v[50:53], v[144:147]
	v_mfma_f32_16x16x32_bf16 v[148:151], v[216:219], v[54:57], v[148:151]
	ds_read_b128 v[216:219], v95 offset:6144
	s_waitcnt lgkmcnt(3)
	v_mfma_f32_16x16x32_bf16 v[152:155], v[204:207], v[58:61], v[90:93]
	v_mfma_f32_16x16x32_bf16 v[156:159], v[204:207], v[62:65], v[90:93]
	s_waitcnt lgkmcnt(2)
	v_mfma_f32_16x16x32_bf16 v[152:155], v[208:211], v[50:53], v[152:155]
	v_mfma_f32_16x16x32_bf16 v[156:159], v[208:211], v[54:57], v[156:159]
	s_waitcnt lgkmcnt(1)
	v_mfma_f32_16x16x32_bf16 v[160:163], v[212:215], v[58:61], v[90:93]
	v_mfma_f32_16x16x32_bf16 v[164:167], v[212:215], v[62:65], v[90:93]
	s_waitcnt lgkmcnt(0)
	v_mfma_f32_16x16x32_bf16 v[160:163], v[216:219], v[50:53], v[160:163]
	v_mfma_f32_16x16x32_bf16 v[164:167], v[216:219], v[54:57], v[164:167]
	s_nop 7
	v_exp_f32_e32 v136, v136
	v_exp_f32_e32 v137, v137
	v_exp_f32_e32 v138, v138
	v_exp_f32_e32 v139, v139
	v_exp_f32_e32 v144, v144
	v_exp_f32_e32 v145, v145
	v_exp_f32_e32 v146, v146
	v_exp_f32_e32 v147, v147
	v_exp_f32_e32 v140, v140
	v_exp_f32_e32 v141, v141
	v_exp_f32_e32 v142, v142
	v_exp_f32_e32 v143, v143
	v_exp_f32_e32 v148, v148
	v_exp_f32_e32 v149, v149
	v_exp_f32_e32 v150, v150
	v_exp_f32_e32 v151, v151
	v_cvt_pk_bf16_f32 v136, v136, v137
	v_cvt_pk_bf16_f32 v137, v138, v139
	v_cvt_pk_bf16_f32 v138, v144, v145
	v_cvt_pk_bf16_f32 v139, v146, v147
	v_cvt_pk_bf16_f32 v140, v140, v141
	v_cvt_pk_bf16_f32 v141, v142, v143
	v_cvt_pk_bf16_f32 v142, v148, v149
	v_cvt_pk_bf16_f32 v143, v150, v151
	s_waitcnt vmcnt(0) lgkmcnt(0)
	s_barrier
.Lattn_loop:
	v_add3_u32 v94, s20, v134, v133
	v_add3_u32 v95, s20, v134, v132
	ds_read_b128 v[204:207], v94
	ds_read_b128 v[208:211], v95
	ds_read_b128 v[212:215], v94 offset:2048
	ds_read_b128 v[216:219], v95 offset:2048
	v_add_u32_e32 v96, s21, v133
	v_add_u32_e32 v97, s21, v132
	s_add_i32 s25, s4, s22
	s_waitcnt lgkmcnt(3)
	v_mfma_f32_16x16x32_bf16 v[168:171], v[204:207], v[58:61], v[90:93]
	s_mov_b32 m0, s25
	s_nop 0
	global_load_lds_dwordx4 v[248:249], off
	v_mfma_f32_16x16x32_bf16 v[172:175], v[204:207], v[62:65], v[90:93]
	ds_read_b128 v[204:207], v94 offset:4096
	s_waitcnt lgkmcnt(3)
	v_mfma_f32_16x16x32_bf16 v[168:171], v[208:211], v[50:53], v[168:171]
	v_mfma_f32_16x16x32_bf16 v[172:175], v[208:211], v[54:57], v[172:175]
	ds_read_b128 v[208:211], v95 offset:4096
	s_waitcnt lgkmcnt(3)
	v_mfma_f32_16x16x32_bf16 v[176:179], v[212:215], v[58:61], v[90:93]
	s_add_i32 m0, s25, 0x2000
	s_nop 0
	global_load_lds_dwordx4 v[250:251], off
	v_mfma_f32_16x16x32_bf16 v[180:183], v[212:215], v[62:65], v[90:93]
	ds_read_b128 v[212:215], v94 offset:6144
	s_waitcnt lgkmcnt(3)
	v_mfma_f32_16x16x32_bf16 v[176:179], v[216:219], v[50:53], v[176:179]
	v_mfma_f32_16x16x32_bf16 v[180:183], v[216:219], v[54:57], v[180:183]
	ds_read_b128 v[216:219], v95 offset:6144
	s_waitcnt lgkmcnt(3)
	v_mfma_f32_16x16x32_bf16 v[184:187], v[204:207], v[58:61], v[90:93]
	s_add_i32 m0, s25, 0x4000
	s_nop 0
	global_load_lds_dwordx4 v[252:253], off
	v_mfma_f32_16x16x32_bf16 v[188:191], v[204:207], v[62:65], v[90:93]
	ds_read_b128 v[220:223], v96 offset:16384
	s_waitcnt lgkmcnt(3)
	v_mfma_f32_16x16x32_bf16 v[184:187], v[208:211], v[50:53], v[184:187]
	ds_read_b128 v[224:227], v96 offset:18432
	v_mfma_f32_16x16x32_bf16 v[188:191], v[208:211], v[54:57], v[188:191]
	ds_read_b128 v[228:231], v96 offset:20480
	s_waitcnt lgkmcnt(4)
	v_mfma_f32_16x16x32_bf16 v[192:195], v[212:215], v[58:61], v[90:93]
	s_add_i32 m0, s25, 0x6000
	s_nop 0
	global_load_lds_dwordx4 v[254:255], off
	ds_read_b128 v[232:235], v96 offset:22528
	v_mfma_f32_16x16x32_bf16 v[200:203], v[212:215], v[62:65], v[90:93]
	s_waitcnt lgkmcnt(4)
	v_mfma_f32_16x16x32_bf16 v[192:195], v[216:219], v[50:53], v[192:195]
	v_lshl_add_u64 v[248:249], v[248:249], 0, s[6:7]
	v_lshl_add_u64 v[250:251], v[250:251], 0, s[6:7]
	v_mfma_f32_16x16x32_bf16 v[200:203], v[216:219], v[54:57], v[200:203]
	v_lshl_add_u64 v[252:253], v[252:253], 0, s[2:3]
	v_lshl_add_u64 v[254:255], v[254:255], 0, s[2:3]
	v_mfma_f32_16x16x32_bf16 v[86:89], v[244:247], v[136:139], v[86:89]
	v_exp_f32_e32 v152, v152
	ds_read_b128 v[236:239], v96 offset:24576
	v_mfma_f32_16x16x32_bf16 v[82:85], v[244:247], v[140:143], v[82:85]
	v_exp_f32_e32 v153, v153
	ds_read_b128 v[240:243], v96 offset:26624
	s_waitcnt lgkmcnt(5)
	v_mfma_f32_16x16x32_bf16 v[78:81], v[220:223], v[136:139], v[78:81]
	v_exp_f32_e32 v154, v154
	v_mfma_f32_16x16x32_bf16 v[74:77], v[220:223], v[140:143], v[74:77]
	v_exp_f32_e32 v155, v155
	ds_read_b128 v[220:223], v96 offset:28672
	s_waitcnt lgkmcnt(5)
	v_mfma_f32_16x16x32_bf16 v[70:73], v[224:227], v[136:139], v[70:73]
	v_exp_f32_e32 v160, v160
	v_mfma_f32_16x16x32_bf16 v[66:69], v[224:227], v[140:143], v[66:69]
	v_exp_f32_e32 v161, v161
	ds_read_b128 v[224:227], v96 offset:30720
	s_waitcnt lgkmcnt(5)
	v_mfma_f32_16x16x32_bf16 v[46:49], v[228:231], v[136:139], v[46:49]
	v_exp_f32_e32 v162, v162
	v_mfma_f32_16x16x32_bf16 v[42:45], v[228:231], v[140:143], v[42:45]
	v_exp_f32_e32 v163, v163
	ds_read_b128 v[228:231], v97 offset:16384
	s_waitcnt lgkmcnt(5)
	v_mfma_f32_16x16x32_bf16 v[38:41], v[232:235], v[136:139], v[38:41]
	v_exp_f32_e32 v156, v156
	v_cvt_pk_bf16_f32 v152, v152, v153
	v_mfma_f32_16x16x32_bf16 v[34:37], v[232:235], v[140:143], v[34:37]
	v_exp_f32_e32 v157, v157
	v_cvt_pk_bf16_f32 v153, v154, v155
	ds_read_b128 v[232:235], v97 offset:18432
	s_waitcnt lgkmcnt(5)
	v_mfma_f32_16x16x32_bf16 v[30:33], v[236:239], v[136:139], v[30:33]
	v_exp_f32_e32 v158, v158
	v_cvt_pk_bf16_f32 v154, v160, v161
	v_mfma_f32_16x16x32_bf16 v[26:29], v[236:239], v[140:143], v[26:29]
	v_exp_f32_e32 v159, v159
	v_cvt_pk_bf16_f32 v155, v162, v163
	ds_read_b128 v[236:239], v97 offset:20480
	s_waitcnt lgkmcnt(5)
	v_mfma_f32_16x16x32_bf16 v[18:21], v[240:243], v[136:139], v[18:21]
	v_exp_f32_e32 v164, v164
	v_cvt_pk_bf16_f32 v156, v156, v157
	v_mfma_f32_16x16x32_bf16 v[10:13], v[240:243], v[140:143], v[10:13]
	v_exp_f32_e32 v165, v165
	v_cvt_pk_bf16_f32 v157, v158, v159
	ds_read_b128 v[240:243], v97 offset:22528
	s_waitcnt lgkmcnt(5)
	v_mfma_f32_16x16x32_bf16 v[6:9], v[220:223], v[136:139], v[6:9]
	v_exp_f32_e32 v166, v166
	v_cvt_pk_bf16_f32 v158, v164, v165
	v_mfma_f32_16x16x32_bf16 v[2:5], v[220:223], v[140:143], v[2:5]
	v_exp_f32_e32 v167, v167
	ds_read_b128 v[220:223], v97 offset:24576
	s_waitcnt lgkmcnt(5)
	v_mfma_f32_16x16x32_bf16 v[14:17], v[224:227], v[136:139], v[14:17]
	v_cvt_pk_bf16_f32 v159, v166, v167
	v_mfma_f32_16x16x32_bf16 v[22:25], v[224:227], v[140:143], v[22:25]
	ds_read_b128 v[224:227], v97 offset:26624
	v_mfma_f32_16x16x32_bf16 v[86:89], v[244:247], v[152:155], v[86:89]
	v_exp_f32_e32 v168, v168
	v_mfma_f32_16x16x32_bf16 v[82:85], v[244:247], v[156:159], v[82:85]
	v_exp_f32_e32 v169, v169
	s_waitcnt lgkmcnt(5)
	v_mfma_f32_16x16x32_bf16 v[78:81], v[228:231], v[152:155], v[78:81]
	v_exp_f32_e32 v170, v170
	v_mfma_f32_16x16x32_bf16 v[74:77], v[228:231], v[156:159], v[74:77]
	v_exp_f32_e32 v171, v171
	ds_read_b128 v[228:231], v97 offset:28672
	s_waitcnt lgkmcnt(5)
	v_mfma_f32_16x16x32_bf16 v[70:73], v[232:235], v[152:155], v[70:73]
	v_exp_f32_e32 v176, v176
	v_mfma_f32_16x16x32_bf16 v[66:69], v[232:235], v[156:159], v[66:69]
	v_exp_f32_e32 v177, v177
	ds_read_b128 v[232:235], v97 offset:30720
	s_waitcnt lgkmcnt(5)
	v_mfma_f32_16x16x32_bf16 v[46:49], v[236:239], v[152:155], v[46:49]
	v_exp_f32_e32 v178, v178
	v_mfma_f32_16x16x32_bf16 v[42:45], v[236:239], v[156:159], v[42:45]
	v_exp_f32_e32 v179, v179
	s_waitcnt lgkmcnt(4)
	v_mfma_f32_16x16x32_bf16 v[38:41], v[240:243], v[152:155], v[38:41]
	v_exp_f32_e32 v172, v172
	v_mfma_f32_16x16x32_bf16 v[34:37], v[240:243], v[156:159], v[34:37]
	v_exp_f32_e32 v173, v173
	v_cvt_pk_bf16_f32 v168, v168, v169
	s_waitcnt lgkmcnt(3)
	v_mfma_f32_16x16x32_bf16 v[30:33], v[220:223], v[152:155], v[30:33]
	v_exp_f32_e32 v174, v174
	v_cvt_pk_bf16_f32 v169, v170, v171
	v_mfma_f32_16x16x32_bf16 v[26:29], v[220:223], v[156:159], v[26:29]
	v_exp_f32_e32 v175, v175
	v_cvt_pk_bf16_f32 v170, v176, v177
	s_waitcnt lgkmcnt(2)
	v_mfma_f32_16x16x32_bf16 v[18:21], v[224:227], v[152:155], v[18:21]
	v_exp_f32_e32 v180, v180
	v_cvt_pk_bf16_f32 v171, v178, v179
	v_mfma_f32_16x16x32_bf16 v[10:13], v[224:227], v[156:159], v[10:13]
	v_exp_f32_e32 v181, v181
	s_waitcnt lgkmcnt(1)
	v_mfma_f32_16x16x32_bf16 v[6:9], v[228:231], v[152:155], v[6:9]
	v_exp_f32_e32 v182, v182
	v_mfma_f32_16x16x32_bf16 v[2:5], v[228:231], v[156:159], v[2:5]
	v_exp_f32_e32 v183, v183
	s_waitcnt lgkmcnt(0)
	v_mfma_f32_16x16x32_bf16 v[14:17], v[232:235], v[152:155], v[14:17]
	v_cvt_pk_bf16_f32 v172, v172, v173
	v_cvt_pk_bf16_f32 v173, v174, v175
	v_mfma_f32_16x16x32_bf16 v[22:25], v[232:235], v[156:159], v[22:25]
	v_cvt_pk_bf16_f32 v174, v180, v181
	v_cvt_pk_bf16_f32 v175, v182, v183
	s_waitcnt vmcnt(0) lgkmcnt(0)
	s_barrier
	s_mov_b32 s24, s21
	s_mov_b32 s21, s20
	s_mov_b32 s20, s22
	s_mov_b32 s22, s24
	v_add3_u32 v94, s20, v134, v133
	v_add3_u32 v95, s20, v134, v132
	ds_read_b128 v[204:207], v94
	ds_read_b128 v[208:211], v95
	ds_read_b128 v[212:215], v94 offset:2048
	ds_read_b128 v[216:219], v95 offset:2048
	v_add_u32_e32 v96, s21, v133
	v_add_u32_e32 v97, s21, v132
	s_add_i32 s25, s4, s22
	s_waitcnt lgkmcnt(3)
	v_mfma_f32_16x16x32_bf16 v[136:139], v[204:207], v[58:61], v[90:93]
	s_mov_b32 m0, s25
	s_nop 0
	global_load_lds_dwordx4 v[248:249], off
	v_mfma_f32_16x16x32_bf16 v[140:143], v[204:207], v[62:65], v[90:93]
	ds_read_b128 v[204:207], v94 offset:4096
	s_waitcnt lgkmcnt(3)
	v_mfma_f32_16x16x32_bf16 v[136:139], v[208:211], v[50:53], v[136:139]
	v_mfma_f32_16x16x32_bf16 v[140:143], v[208:211], v[54:57], v[140:143]
	ds_read_b128 v[208:211], v95 offset:4096
	s_waitcnt lgkmcnt(3)
	v_mfma_f32_16x16x32_bf16 v[144:147], v[212:215], v[58:61], v[90:93]
	s_add_i32 m0, s25, 0x2000
	s_nop 0
	global_load_lds_dwordx4 v[250:251], off
	v_mfma_f32_16x16x32_bf16 v[148:151], v[212:215], v[62:65], v[90:93]
	ds_read_b128 v[212:215], v94 offset:6144
	s_waitcnt lgkmcnt(3)
	v_mfma_f32_16x16x32_bf16 v[144:147], v[216:219], v[50:53], v[144:147]
	v_mfma_f32_16x16x32_bf16 v[148:151], v[216:219], v[54:57], v[148:151]
	ds_read_b128 v[216:219], v95 offset:6144
	s_waitcnt lgkmcnt(3)
	v_mfma_f32_16x16x32_bf16 v[152:155], v[204:207], v[58:61], v[90:93]
	s_add_i32 m0, s25, 0x4000
	s_nop 0
	global_load_lds_dwordx4 v[252:253], off
	v_mfma_f32_16x16x32_bf16 v[156:159], v[204:207], v[62:65], v[90:93]
	ds_read_b128 v[220:223], v96 offset:16384
	s_waitcnt lgkmcnt(3)
	v_mfma_f32_16x16x32_bf16 v[152:155], v[208:211], v[50:53], v[152:155]
	ds_read_b128 v[224:227], v96 offset:18432
	v_mfma_f32_16x16x32_bf16 v[156:159], v[208:211], v[54:57], v[156:159]
	ds_read_b128 v[228:231], v96 offset:20480
	s_waitcnt lgkmcnt(4)
	v_mfma_f32_16x16x32_bf16 v[160:163], v[212:215], v[58:61], v[90:93]
	s_add_i32 m0, s25, 0x6000
	s_nop 0
	global_load_lds_dwordx4 v[254:255], off
	ds_read_b128 v[232:235], v96 offset:22528
	v_mfma_f32_16x16x32_bf16 v[164:167], v[212:215], v[62:65], v[90:93]
	s_waitcnt lgkmcnt(4)
	v_mfma_f32_16x16x32_bf16 v[160:163], v[216:219], v[50:53], v[160:163]
	v_lshl_add_u64 v[248:249], v[248:249], 0, s[6:7]
	v_lshl_add_u64 v[250:251], v[250:251], 0, s[6:7]
	v_mfma_f32_16x16x32_bf16 v[164:167], v[216:219], v[54:57], v[164:167]
	v_lshl_add_u64 v[252:253], v[252:253], 0, s[2:3]
	v_lshl_add_u64 v[254:255], v[254:255], 0, s[2:3]
	v_mfma_f32_16x16x32_bf16 v[86:89], v[244:247], v[168:171], v[86:89]
	v_exp_f32_e32 v184, v184
	ds_read_b128 v[236:239], v96 offset:24576
	v_mfma_f32_16x16x32_bf16 v[82:85], v[244:247], v[172:175], v[82:85]
	v_exp_f32_e32 v185, v185
	ds_read_b128 v[240:243], v96 offset:26624
	s_waitcnt lgkmcnt(5)
	v_mfma_f32_16x16x32_bf16 v[78:81], v[220:223], v[168:171], v[78:81]
	v_exp_f32_e32 v186, v186
	v_mfma_f32_16x16x32_bf16 v[74:77], v[220:223], v[172:175], v[74:77]
	v_exp_f32_e32 v187, v187
	ds_read_b128 v[220:223], v96 offset:28672
	s_waitcnt lgkmcnt(5)
	v_mfma_f32_16x16x32_bf16 v[70:73], v[224:227], v[168:171], v[70:73]
	v_exp_f32_e32 v192, v192
	v_mfma_f32_16x16x32_bf16 v[66:69], v[224:227], v[172:175], v[66:69]
	v_exp_f32_e32 v193, v193
	ds_read_b128 v[224:227], v96 offset:30720
	s_waitcnt lgkmcnt(5)
	v_mfma_f32_16x16x32_bf16 v[46:49], v[228:231], v[168:171], v[46:49]
	v_exp_f32_e32 v194, v194
	v_mfma_f32_16x16x32_bf16 v[42:45], v[228:231], v[172:175], v[42:45]
	v_exp_f32_e32 v195, v195
	ds_read_b128 v[228:231], v97 offset:16384
	s_waitcnt lgkmcnt(5)
	v_mfma_f32_16x16x32_bf16 v[38:41], v[232:235], v[168:171], v[38:41]
	v_exp_f32_e32 v188, v188
	v_cvt_pk_bf16_f32 v184, v184, v185
	v_mfma_f32_16x16x32_bf16 v[34:37], v[232:235], v[172:175], v[34:37]
	v_exp_f32_e32 v189, v189
	v_cvt_pk_bf16_f32 v185, v186, v187
	ds_read_b128 v[232:235], v97 offset:18432
	s_waitcnt lgkmcnt(5)
	v_mfma_f32_16x16x32_bf16 v[30:33], v[236:239], v[168:171], v[30:33]
	v_exp_f32_e32 v190, v190
	v_cvt_pk_bf16_f32 v186, v192, v193
	v_mfma_f32_16x16x32_bf16 v[26:29], v[236:239], v[172:175], v[26:29]
	v_exp_f32_e32 v191, v191
	v_cvt_pk_bf16_f32 v187, v194, v195
	ds_read_b128 v[236:239], v97 offset:20480
	s_waitcnt lgkmcnt(5)
	v_mfma_f32_16x16x32_bf16 v[18:21], v[240:243], v[168:171], v[18:21]
	v_exp_f32_e32 v200, v200
	v_cvt_pk_bf16_f32 v188, v188, v189
	v_mfma_f32_16x16x32_bf16 v[10:13], v[240:243], v[172:175], v[10:13]
	v_exp_f32_e32 v201, v201
	v_cvt_pk_bf16_f32 v189, v190, v191
	ds_read_b128 v[240:243], v97 offset:22528
	s_waitcnt lgkmcnt(5)
	v_mfma_f32_16x16x32_bf16 v[6:9], v[220:223], v[168:171], v[6:9]
	v_exp_f32_e32 v202, v202
	v_cvt_pk_bf16_f32 v190, v200, v201
	v_mfma_f32_16x16x32_bf16 v[2:5], v[220:223], v[172:175], v[2:5]
	v_exp_f32_e32 v203, v203
	ds_read_b128 v[220:223], v97 offset:24576
	s_waitcnt lgkmcnt(5)
	v_mfma_f32_16x16x32_bf16 v[14:17], v[224:227], v[168:171], v[14:17]
	v_cvt_pk_bf16_f32 v191, v202, v203
	v_mfma_f32_16x16x32_bf16 v[22:25], v[224:227], v[172:175], v[22:25]
	ds_read_b128 v[224:227], v97 offset:26624
	v_mfma_f32_16x16x32_bf16 v[86:89], v[244:247], v[184:187], v[86:89]
	v_exp_f32_e32 v136, v136
	v_mfma_f32_16x16x32_bf16 v[82:85], v[244:247], v[188:191], v[82:85]
	v_exp_f32_e32 v137, v137
	s_waitcnt lgkmcnt(5)
	v_mfma_f32_16x16x32_bf16 v[78:81], v[228:231], v[184:187], v[78:81]
	v_exp_f32_e32 v138, v138
	v_mfma_f32_16x16x32_bf16 v[74:77], v[228:231], v[188:191], v[74:77]
	v_exp_f32_e32 v139, v139
	ds_read_b128 v[228:231], v97 offset:28672
	s_waitcnt lgkmcnt(5)
	v_mfma_f32_16x16x32_bf16 v[70:73], v[232:235], v[184:187], v[70:73]
	v_exp_f32_e32 v144, v144
	v_mfma_f32_16x16x32_bf16 v[66:69], v[232:235], v[188:191], v[66:69]
	v_exp_f32_e32 v145, v145
	ds_read_b128 v[232:235], v97 offset:30720
	s_waitcnt lgkmcnt(5)
	v_mfma_f32_16x16x32_bf16 v[46:49], v[236:239], v[184:187], v[46:49]
	v_exp_f32_e32 v146, v146
	v_mfma_f32_16x16x32_bf16 v[42:45], v[236:239], v[188:191], v[42:45]
	v_exp_f32_e32 v147, v147
	s_waitcnt lgkmcnt(4)
	v_mfma_f32_16x16x32_bf16 v[38:41], v[240:243], v[184:187], v[38:41]
	v_exp_f32_e32 v140, v140
	v_mfma_f32_16x16x32_bf16 v[34:37], v[240:243], v[188:191], v[34:37]
	v_exp_f32_e32 v141, v141
	v_cvt_pk_bf16_f32 v136, v136, v137
	s_waitcnt lgkmcnt(3)
	v_mfma_f32_16x16x32_bf16 v[30:33], v[220:223], v[184:187], v[30:33]
	v_exp_f32_e32 v142, v142
	v_cvt_pk_bf16_f32 v137, v138, v139
	v_mfma_f32_16x16x32_bf16 v[26:29], v[220:223], v[188:191], v[26:29]
	v_exp_f32_e32 v143, v143
	v_cvt_pk_bf16_f32 v138, v144, v145
	s_waitcnt lgkmcnt(2)
	v_mfma_f32_16x16x32_bf16 v[18:21], v[224:227], v[184:187], v[18:21]
	v_exp_f32_e32 v148, v148
	v_cvt_pk_bf16_f32 v139, v146, v147
	v_mfma_f32_16x16x32_bf16 v[10:13], v[224:227], v[188:191], v[10:13]
	v_exp_f32_e32 v149, v149
	s_waitcnt lgkmcnt(1)
	v_mfma_f32_16x16x32_bf16 v[6:9], v[228:231], v[184:187], v[6:9]
	v_exp_f32_e32 v150, v150
	v_mfma_f32_16x16x32_bf16 v[2:5], v[228:231], v[188:191], v[2:5]
	v_exp_f32_e32 v151, v151
	s_waitcnt lgkmcnt(0)
	v_mfma_f32_16x16x32_bf16 v[14:17], v[232:235], v[184:187], v[14:17]
	v_cvt_pk_bf16_f32 v140, v140, v141
	v_cvt_pk_bf16_f32 v141, v142, v143
	v_mfma_f32_16x16x32_bf16 v[22:25], v[232:235], v[188:191], v[22:25]
	v_cvt_pk_bf16_f32 v142, v148, v149
	v_cvt_pk_bf16_f32 v143, v150, v151
	s_waitcnt vmcnt(0) lgkmcnt(0)
	s_barrier
	s_mov_b32 s24, s21
	s_mov_b32 s21, s20
	s_mov_b32 s20, s22
	s_mov_b32 s22, s24
	s_add_i32 s23, s23, 1
	s_cmp_lg_u32 s23, 33
	s_cbranch_scc1 .Lattn_loop
	v_add_u32_e32 v96, s21, v133
	v_add_u32_e32 v97, s21, v132
	ds_read_b128 v[220:223], v96 offset:16384
	ds_read_b128 v[224:227], v96 offset:18432
	ds_read_b128 v[228:231], v96 offset:20480
	ds_read_b128 v[232:235], v96 offset:22528
	v_mfma_f32_16x16x32_bf16 v[86:89], v[244:247], v[136:139], v[86:89]
	v_exp_f32_e32 v152, v152
	ds_read_b128 v[236:239], v96 offset:24576
	v_mfma_f32_16x16x32_bf16 v[82:85], v[244:247], v[140:143], v[82:85]
	v_exp_f32_e32 v153, v153
	ds_read_b128 v[240:243], v96 offset:26624
	s_waitcnt lgkmcnt(5)
	v_mfma_f32_16x16x32_bf16 v[78:81], v[220:223], v[136:139], v[78:81]
	v_exp_f32_e32 v154, v154
	v_mfma_f32_16x16x32_bf16 v[74:77], v[220:223], v[140:143], v[74:77]
	v_exp_f32_e32 v155, v155
	ds_read_b128 v[220:223], v96 offset:28672
	s_waitcnt lgkmcnt(5)
	v_mfma_f32_16x16x32_bf16 v[70:73], v[224:227], v[136:139], v[70:73]
	v_exp_f32_e32 v160, v160
	v_mfma_f32_16x16x32_bf16 v[66:69], v[224:227], v[140:143], v[66:69]
	v_exp_f32_e32 v161, v161
	ds_read_b128 v[224:227], v96 offset:30720
	s_waitcnt lgkmcnt(5)
	v_mfma_f32_16x16x32_bf16 v[46:49], v[228:231], v[136:139], v[46:49]
	v_exp_f32_e32 v162, v162
	v_mfma_f32_16x16x32_bf16 v[42:45], v[228:231], v[140:143], v[42:45]
	v_exp_f32_e32 v163, v163
	ds_read_b128 v[228:231], v97 offset:16384
	s_waitcnt lgkmcnt(5)
	v_mfma_f32_16x16x32_bf16 v[38:41], v[232:235], v[136:139], v[38:41]
	v_exp_f32_e32 v156, v156
	v_cvt_pk_bf16_f32 v152, v152, v153
	v_mfma_f32_16x16x32_bf16 v[34:37], v[232:235], v[140:143], v[34:37]
	v_exp_f32_e32 v157, v157
	v_cvt_pk_bf16_f32 v153, v154, v155
	ds_read_b128 v[232:235], v97 offset:18432
	s_waitcnt lgkmcnt(5)
	v_mfma_f32_16x16x32_bf16 v[30:33], v[236:239], v[136:139], v[30:33]
	v_exp_f32_e32 v158, v158
	v_cvt_pk_bf16_f32 v154, v160, v161
	v_mfma_f32_16x16x32_bf16 v[26:29], v[236:239], v[140:143], v[26:29]
	v_exp_f32_e32 v159, v159
	v_cvt_pk_bf16_f32 v155, v162, v163
	ds_read_b128 v[236:239], v97 offset:20480
	s_waitcnt lgkmcnt(5)
	v_mfma_f32_16x16x32_bf16 v[18:21], v[240:243], v[136:139], v[18:21]
	v_exp_f32_e32 v164, v164
	v_cvt_pk_bf16_f32 v156, v156, v157
	v_mfma_f32_16x16x32_bf16 v[10:13], v[240:243], v[140:143], v[10:13]
	v_exp_f32_e32 v165, v165
	v_cvt_pk_bf16_f32 v157, v158, v159
	ds_read_b128 v[240:243], v97 offset:22528
	s_waitcnt lgkmcnt(5)
	v_mfma_f32_16x16x32_bf16 v[6:9], v[220:223], v[136:139], v[6:9]
	v_exp_f32_e32 v166, v166
	v_cvt_pk_bf16_f32 v158, v164, v165
	v_mfma_f32_16x16x32_bf16 v[2:5], v[220:223], v[140:143], v[2:5]
	v_exp_f32_e32 v167, v167
	ds_read_b128 v[220:223], v97 offset:24576
	s_waitcnt lgkmcnt(5)
	v_mfma_f32_16x16x32_bf16 v[14:17], v[224:227], v[136:139], v[14:17]
	v_cvt_pk_bf16_f32 v159, v166, v167
	v_mfma_f32_16x16x32_bf16 v[22:25], v[224:227], v[140:143], v[22:25]
	ds_read_b128 v[224:227], v97 offset:26624
	v_mfma_f32_16x16x32_bf16 v[86:89], v[244:247], v[152:155], v[86:89]
	v_mfma_f32_16x16x32_bf16 v[82:85], v[244:247], v[156:159], v[82:85]
	s_waitcnt lgkmcnt(5)
	v_mfma_f32_16x16x32_bf16 v[78:81], v[228:231], v[152:155], v[78:81]
	v_mfma_f32_16x16x32_bf16 v[74:77], v[228:231], v[156:159], v[74:77]
	ds_read_b128 v[228:231], v97 offset:28672
	s_waitcnt lgkmcnt(5)
	v_mfma_f32_16x16x32_bf16 v[70:73], v[232:235], v[152:155], v[70:73]
	v_mfma_f32_16x16x32_bf16 v[66:69], v[232:235], v[156:159], v[66:69]
	ds_read_b128 v[232:235], v97 offset:30720
	s_waitcnt lgkmcnt(5)
	v_mfma_f32_16x16x32_bf16 v[46:49], v[236:239], v[152:155], v[46:49]
	v_mfma_f32_16x16x32_bf16 v[42:45], v[236:239], v[156:159], v[42:45]
	s_waitcnt lgkmcnt(4)
	v_mfma_f32_16x16x32_bf16 v[38:41], v[240:243], v[152:155], v[38:41]
	v_mfma_f32_16x16x32_bf16 v[34:37], v[240:243], v[156:159], v[34:37]
	s_waitcnt lgkmcnt(3)
	v_mfma_f32_16x16x32_bf16 v[30:33], v[220:223], v[152:155], v[30:33]
	v_mfma_f32_16x16x32_bf16 v[26:29], v[220:223], v[156:159], v[26:29]
	s_waitcnt lgkmcnt(2)
	v_mfma_f32_16x16x32_bf16 v[18:21], v[224:227], v[152:155], v[18:21]
	v_mfma_f32_16x16x32_bf16 v[10:13], v[224:227], v[156:159], v[10:13]
	s_waitcnt lgkmcnt(1)
	v_mfma_f32_16x16x32_bf16 v[6:9], v[228:231], v[152:155], v[6:9]
	v_mfma_f32_16x16x32_bf16 v[2:5], v[228:231], v[156:159], v[2:5]
	s_waitcnt lgkmcnt(0)
	v_mfma_f32_16x16x32_bf16 v[14:17], v[232:235], v[152:155], v[14:17]
	v_mfma_f32_16x16x32_bf16 v[22:25], v[232:235], v[156:159], v[22:25]
	s_waitcnt lgkmcnt(0)

	v_add_u32_e32 v98, 0, v134
	v_add_u32_e32 v154, v98, v133
	ds_read_b128 v[94:97], v154 offset:32768
	v_add_u32_e32 v98, v98, v132
	ds_read_b128 v[134:137], v98 offset:32768
	ds_read_b128 v[142:145], v98 offset:34816
	ds_read_b128 v[150:153], v98 offset:36864
	s_waitcnt lgkmcnt(3)
	v_mfma_f32_16x16x32_bf16 v[110:113], v[94:97], v[58:61], v[90:93]
	v_mfma_f32_16x16x32_bf16 v[94:97], v[94:97], v[62:65], v[90:93]
	s_waitcnt lgkmcnt(2)
	v_mfma_f32_16x16x32_bf16 v[110:113], v[134:137], v[50:53], v[110:113]
	v_mfma_f32_16x16x32_bf16 v[94:97], v[134:137], v[54:57], v[94:97]
	ds_read_b128 v[134:137], v154 offset:34816
	s_waitcnt lgkmcnt(0)
	v_mfma_f32_16x16x32_bf16 v[138:141], v[134:137], v[58:61], v[90:93]
	v_mfma_f32_16x16x32_bf16 v[134:137], v[134:137], v[62:65], v[90:93]
	v_mfma_f32_16x16x32_bf16 v[138:141], v[142:145], v[50:53], v[138:141]
	v_mfma_f32_16x16x32_bf16 v[134:137], v[142:145], v[54:57], v[134:137]
	ds_read_b128 v[142:145], v154 offset:36864
	s_waitcnt lgkmcnt(0)
	v_mfma_f32_16x16x32_bf16 v[146:149], v[142:145], v[58:61], v[90:93]
	v_mfma_f32_16x16x32_bf16 v[142:145], v[142:145], v[62:65], v[90:93]
	v_mfma_f32_16x16x32_bf16 v[146:149], v[150:153], v[50:53], v[146:149]
	v_mfma_f32_16x16x32_bf16 v[142:145], v[150:153], v[54:57], v[142:145]
	ds_read_b128 v[150:153], v154 offset:38912
	s_waitcnt lgkmcnt(0)
	v_mfma_f32_16x16x32_bf16 v[58:61], v[150:153], v[58:61], v[90:93]
	v_mfma_f32_16x16x32_bf16 v[62:65], v[150:153], v[62:65], v[90:93]
	s_nop 2
	ds_read_b128 v[90:93], v98 offset:38912
	s_waitcnt lgkmcnt(0)
	v_mfma_f32_16x16x32_bf16 v[50:53], v[90:93], v[50:53], v[58:61]
	v_mfma_f32_16x16x32_bf16 v[60:63], v[90:93], v[54:57], v[62:65]
	v_exp_f32_e32 v54, v110
	v_exp_f32_e32 v55, v111
	v_exp_f32_e32 v56, v112
	v_exp_f32_e32 v57, v113
	v_exp_f32_e32 v58, v138
	v_exp_f32_e32 v59, v139
	v_exp_f32_e32 v64, v140
	v_exp_f32_e32 v65, v141
	v_exp_f32_e32 v98, v146
	v_exp_f32_e32 v110, v147
	v_exp_f32_e32 v111, v148
	v_exp_f32_e32 v112, v149
	v_exp_f32_e32 v50, v50
	v_exp_f32_e32 v51, v51
	v_exp_f32_e32 v52, v52
	v_exp_f32_e32 v53, v53
	v_cvt_pk_bf16_f32 v90, v54, v55
	v_cvt_pk_bf16_f32 v91, v56, v57
	v_cvt_pk_bf16_f32 v92, v58, v59
	v_cvt_pk_bf16_f32 v93, v64, v65
	v_cvt_pk_bf16_f32 v56, v98, v110
	v_cvt_pk_bf16_f32 v57, v111, v112
	v_cvt_pk_bf16_f32 v58, v50, v51
	v_cvt_pk_bf16_f32 v59, v52, v53
	v_exp_f32_e32 v50, v94
	v_exp_f32_e32 v51, v95
	v_exp_f32_e32 v52, v96
	v_exp_f32_e32 v53, v97
	v_exp_f32_e32 v54, v134
	v_exp_f32_e32 v55, v135
	v_exp_f32_e32 v64, v136
	v_exp_f32_e32 v65, v137
	v_exp_f32_e32 v98, v142
	v_exp_f32_e32 v110, v143
	v_exp_f32_e32 v111, v144
	v_exp_f32_e32 v112, v145
	v_exp_f32_e32 v60, v60
	v_exp_f32_e32 v61, v61
	v_exp_f32_e32 v62, v62
	v_exp_f32_e32 v63, v63
	v_cvt_pk_bf16_f32 v94, v50, v51
	v_cvt_pk_bf16_f32 v95, v52, v53
	v_cvt_pk_bf16_f32 v96, v54, v55
	v_cvt_pk_bf16_f32 v97, v64, v65
	v_cvt_pk_bf16_f32 v110, v98, v110
	v_cvt_pk_bf16_f32 v111, v111, v112
	v_cvt_pk_bf16_f32 v112, v60, v61
	v_cvt_pk_bf16_f32 v113, v62, v63
	v_mov_b64_e32 v[52:53], s[10:11]
	v_mov_b64_e32 v[50:51], s[8:9]
	s_nop 1
	v_mfma_f32_16x16x32_bf16 v[60:63], v[50:53], v[90:93], v[86:89]
	v_mfma_f32_16x16x32_bf16 v[82:85], v[50:53], v[94:97], v[82:85]
	v_mfma_f32_16x16x32_bf16 v[86:89], v[50:53], v[56:59], v[60:63]
	v_mfma_f32_16x16x32_bf16 v[50:53], v[50:53], v[110:113], v[82:85]
	s_nop 6
	v_add_u32_e32 v87, 0, v132
	v_add_u32_e32 v51, 0, v133
	ds_read_b128 v[52:55], v51 offset:49152
	s_waitcnt lgkmcnt(0)
	v_mfma_f32_16x16x32_bf16 v[60:63], v[52:55], v[90:93], v[78:81]
	v_mfma_f32_16x16x32_bf16 v[52:55], v[52:55], v[94:97], v[74:77]
	s_nop 2
	ds_read_b128 v[74:77], v87 offset:49152
	s_waitcnt lgkmcnt(0)
	v_mfma_f32_16x16x32_bf16 v[78:81], v[74:77], v[56:59], v[60:63]
	s_nop 2
	ds_read_b128 v[60:63], v51 offset:51200
	s_waitcnt lgkmcnt(0)
	v_mfma_f32_16x16x32_bf16 v[70:73], v[60:63], v[90:93], v[70:73]
	v_mfma_f32_16x16x32_bf16 v[60:63], v[60:63], v[94:97], v[66:69]
	s_nop 2
	ds_read_b128 v[64:67], v87 offset:51200
	v_mfma_f32_16x16x32_bf16 v[52:55], v[74:77], v[110:113], v[52:55]
	s_waitcnt lgkmcnt(0)
	v_mfma_f32_16x16x32_bf16 v[68:71], v[64:67], v[56:59], v[70:73]
	v_mfma_f32_16x16x32_bf16 v[60:63], v[64:67], v[110:113], v[60:63]
	ds_read_b128 v[64:67], v51 offset:53248
	s_waitcnt lgkmcnt(0)
	v_mfma_f32_16x16x32_bf16 v[46:49], v[64:67], v[90:93], v[46:49]
	v_mfma_f32_16x16x32_bf16 v[42:45], v[64:67], v[94:97], v[42:45]
	ds_read_b128 v[64:67], v87 offset:53248
	s_waitcnt lgkmcnt(0)
	v_mfma_f32_16x16x32_bf16 v[46:49], v[64:67], v[56:59], v[46:49]
	v_mfma_f32_16x16x32_bf16 v[42:45], v[64:67], v[110:113], v[42:45]
	ds_read_b128 v[64:67], v51 offset:55296
	s_waitcnt lgkmcnt(0)
	v_mfma_f32_16x16x32_bf16 v[38:41], v[64:67], v[90:93], v[38:41]
	v_mfma_f32_16x16x32_bf16 v[34:37], v[64:67], v[94:97], v[34:37]
	ds_read_b128 v[64:67], v87 offset:55296
	s_waitcnt lgkmcnt(0)
	v_mfma_f32_16x16x32_bf16 v[38:41], v[64:67], v[56:59], v[38:41]
	v_mfma_f32_16x16x32_bf16 v[34:37], v[64:67], v[110:113], v[34:37]
	ds_read_b128 v[64:67], v51 offset:57344
	s_waitcnt lgkmcnt(0)
	v_mfma_f32_16x16x32_bf16 v[30:33], v[64:67], v[90:93], v[30:33]
	v_mfma_f32_16x16x32_bf16 v[26:29], v[64:67], v[94:97], v[26:29]
	ds_read_b128 v[64:67], v87 offset:57344
	s_waitcnt lgkmcnt(0)
	v_mfma_f32_16x16x32_bf16 v[30:33], v[64:67], v[56:59], v[30:33]
	v_mfma_f32_16x16x32_bf16 v[26:29], v[64:67], v[110:113], v[26:29]
	ds_read_b128 v[64:67], v51 offset:59392
	s_waitcnt lgkmcnt(0)
	v_mfma_f32_16x16x32_bf16 v[18:21], v[64:67], v[90:93], v[18:21]
	v_mfma_f32_16x16x32_bf16 v[10:13], v[64:67], v[94:97], v[10:13]
	ds_read_b128 v[64:67], v87 offset:59392
	s_waitcnt lgkmcnt(0)
	v_mfma_f32_16x16x32_bf16 v[72:75], v[64:67], v[56:59], v[18:21]
	v_mfma_f32_16x16x32_bf16 v[132:135], v[64:67], v[110:113], v[10:13]
	s_nop 3
	ds_read_b128 v[10:13], v51 offset:61440
	s_waitcnt lgkmcnt(0)
	v_mfma_f32_16x16x32_bf16 v[6:9], v[10:13], v[90:93], v[6:9]
	v_mfma_f32_16x16x32_bf16 v[2:5], v[10:13], v[94:97], v[2:5]
	ds_read_b128 v[10:13], v87 offset:61440
	s_waitcnt lgkmcnt(0)
	v_mfma_f32_16x16x32_bf16 v[136:139], v[10:13], v[110:113], v[2:5]
	s_nop 4
	ds_read_b128 v[2:5], v51 offset:63488
	v_mfma_f32_16x16x32_bf16 v[82:85], v[10:13], v[56:59], v[6:9]
	ds_read_b128 v[10:13], v87 offset:63488
	s_waitcnt lgkmcnt(1)
	v_mfma_f32_16x16x32_bf16 v[6:9], v[2:5], v[90:93], v[14:17]
	v_mfma_f32_16x16x32_bf16 v[2:5], v[2:5], v[94:97], v[22:25]
	s_waitcnt lgkmcnt(0)
	v_mfma_f32_16x16x32_bf16 v[22:25], v[10:13], v[56:59], v[6:9]
	v_mfma_f32_16x16x32_bf16 v[88:91], v[10:13], v[110:113], v[2:5]
	s_nop 4
	v_div_scale_f32 v2, s[4:5], v86, v86, 1.0
	v_rcp_f32_e32 v3, v2
	s_barrier
	v_fma_f32 v4, -v2, v3, 1.0
	v_fmac_f32_e32 v3, v4, v3
	v_div_scale_f32 v4, vcc, 1.0, v86, 1.0
	v_mul_f32_e32 v5, v4, v3
	v_fma_f32 v6, -v2, v5, v4
	v_fmac_f32_e32 v5, v6, v3
	v_fma_f32 v2, -v2, v5, v4
	v_div_fmas_f32 v2, v2, v3, v5
	v_div_fixup_f32 v56, v2, v86, 1.0
	v_pk_mul_f32 v[18:19], v[56:57], v[30:31] op_sel_hi:[0,1]
	v_div_scale_f32 v30, s[4:5], v50, v50, 1.0
	v_rcp_f32_e32 v31, v30
	v_pk_mul_f32 v[10:11], v[56:57], v[46:47] op_sel_hi:[0,1]
	v_pk_mul_f32 v[46:47], v[56:57], v[84:85] op_sel_hi:[0,1]
	v_pk_mul_f32 v[84:85], v[56:57], v[22:23] op_sel_hi:[0,1]
	v_fma_f32 v22, -v30, v31, 1.0
	v_fmac_f32_e32 v31, v22, v31
	v_div_scale_f32 v22, vcc, 1.0, v50, 1.0
	v_mul_f32_e32 v23, v22, v31
	v_pk_mul_f32 v[66:67], v[56:57], v[24:25] op_sel_hi:[0,1]
	v_fma_f32 v24, -v30, v23, v22
	v_fmac_f32_e32 v23, v24, v31
	v_fma_f32 v22, -v30, v23, v22
	v_div_fmas_f32 v22, v22, v31, v23
	v_div_fixup_f32 v22, v22, v50, 1.0
	v_pk_mul_f32 v[4:5], v[56:57], v[80:81] op_sel_hi:[0,1]
	v_pk_mul_f32 v[6:7], v[56:57], v[78:79] op_sel_hi:[0,1]
	v_pk_mul_f32 v[2:3], v[56:57], v[70:71] op_sel_hi:[0,1]
	v_pk_mul_f32 v[12:13], v[56:57], v[68:69] op_sel_hi:[0,1]
	v_pk_mul_f32 v[8:9], v[56:57], v[48:49] op_sel_hi:[0,1]
	v_pk_mul_f32 v[16:17], v[56:57], v[40:41] op_sel_hi:[0,1]
	v_pk_mul_f32 v[20:21], v[56:57], v[38:39] op_sel_hi:[0,1]
	v_pk_mul_f32 v[14:15], v[56:57], v[32:33] op_sel_hi:[0,1]
	v_pk_mul_f32 v[48:49], v[56:57], v[74:75] op_sel_hi:[0,1]
	v_pk_mul_f32 v[64:65], v[56:57], v[72:73] op_sel_hi:[0,1]
	v_pk_mul_f32 v[86:87], v[56:57], v[82:83] op_sel_hi:[0,1]
	v_pk_mul_f32 v[54:55], v[22:23], v[54:55] op_sel_hi:[0,1]
	v_pk_mul_f32 v[52:53], v[22:23], v[52:53] op_sel_hi:[0,1]
	v_pk_mul_f32 v[56:57], v[22:23], v[62:63] op_sel_hi:[0,1]
	v_pk_mul_f32 v[58:59], v[22:23], v[60:61] op_sel_hi:[0,1]
	v_pk_mul_f32 v[60:61], v[22:23], v[44:45] op_sel_hi:[0,1]
	v_pk_mul_f32 v[76:77], v[22:23], v[42:43] op_sel_hi:[0,1]
	v_pk_mul_f32 v[68:69], v[22:23], v[36:37] op_sel_hi:[0,1]
	v_pk_mul_f32 v[78:79], v[22:23], v[34:35] op_sel_hi:[0,1]
	v_pk_mul_f32 v[70:71], v[22:23], v[28:29] op_sel_hi:[0,1]
	v_pk_mul_f32 v[72:73], v[22:23], v[26:27] op_sel_hi:[0,1]
	v_pk_mul_f32 v[74:75], v[22:23], v[134:135] op_sel_hi:[0,1]
	v_pk_mul_f32 v[80:81], v[22:23], v[132:133] op_sel_hi:[0,1]
	v_pk_mul_f32 v[40:41], v[22:23], v[138:139] op_sel_hi:[0,1]
	v_pk_mul_f32 v[82:83], v[22:23], v[136:137] op_sel_hi:[0,1]
	v_pk_mul_f32 v[34:35], v[22:23], v[90:91] op_sel_hi:[0,1]
	v_pk_mul_f32 v[42:43], v[22:23], v[88:89] op_sel_hi:[0,1]
	v_cmp_eq_u32_e32 vcc, 1, v127
	s_and_saveexec_b64 s[4:5], vcc
	s_cbranch_execz .LBB0_454
	v_lshlrev_b32_e32 v22, 14, v128
	v_add3_u32 v22, 0, v126, v22
	ds_write2st64_b32 v22, v6, v7 offset1:1
	ds_write2st64_b32 v22, v4, v5 offset0:2 offset1:3
	ds_write2st64_b32 v22, v52, v53 offset0:4 offset1:5
	ds_write2st64_b32 v22, v54, v55 offset0:6 offset1:7
	ds_write2st64_b32 v22, v12, v13 offset0:8 offset1:9
	ds_write2st64_b32 v22, v2, v3 offset0:10 offset1:11
	ds_write2st64_b32 v22, v58, v59 offset0:12 offset1:13
	ds_write2st64_b32 v22, v56, v57 offset0:14 offset1:15
	ds_write2st64_b32 v22, v10, v11 offset0:16 offset1:17
	ds_write2st64_b32 v22, v8, v9 offset0:18 offset1:19
	ds_write2st64_b32 v22, v76, v77 offset0:20 offset1:21
	ds_write2st64_b32 v22, v60, v61 offset0:22 offset1:23
	ds_write2st64_b32 v22, v20, v21 offset0:24 offset1:25
	ds_write2st64_b32 v22, v16, v17 offset0:26 offset1:27
	ds_write2st64_b32 v22, v78, v79 offset0:28 offset1:29
	ds_write2st64_b32 v22, v68, v69 offset0:30 offset1:31
	ds_write2st64_b32 v22, v18, v19 offset0:32 offset1:33
	ds_write2st64_b32 v22, v14, v15 offset0:34 offset1:35
	ds_write2st64_b32 v22, v72, v73 offset0:36 offset1:37
	ds_write2st64_b32 v22, v70, v71 offset0:38 offset1:39
	ds_write2st64_b32 v22, v64, v65 offset0:40 offset1:41
	ds_write2st64_b32 v22, v48, v49 offset0:42 offset1:43
	ds_write2st64_b32 v22, v80, v81 offset0:44 offset1:45
	ds_write2st64_b32 v22, v74, v75 offset0:46 offset1:47
	ds_write2st64_b32 v22, v86, v87 offset0:48 offset1:49
	ds_write2st64_b32 v22, v46, v47 offset0:50 offset1:51
	ds_write2st64_b32 v22, v82, v83 offset0:52 offset1:53
	ds_write2st64_b32 v22, v40, v41 offset0:54 offset1:55
	ds_write2st64_b32 v22, v84, v85 offset0:56 offset1:57
	ds_write2st64_b32 v22, v66, v67 offset0:58 offset1:59
	ds_write2st64_b32 v22, v42, v43 offset0:60 offset1:61
	ds_write2st64_b32 v22, v34, v35 offset0:62 offset1:63
